# store cache policy by consumer distance: P9 gate tiles (consumed two phases later), P7's RWO and the final norm's output get the nt hint; P9 q/k/v tiles stay cached for the attention phase
# baseline (speedup 1.0000x reference)
.LBB0_639:
	v_lshl_add_u64 v[42:43], s[8:9], 0, v[26:27]
	v_lshlrev_b32_e32 v48, 16, v38
	v_and_b32_e32 v50, 0xffff0000, v38
	v_add_co_u32_e64 v38, s[2:3], s35, v42
	v_lshlrev_b32_e32 v54, 16, v39
	v_and_b32_e32 v56, 0xffff0000, v39
	v_addc_co_u32_e64 v39, s[2:3], 0, v43, s[2:3]
	v_add_co_u32_e64 v8, s[2:3], s41, v42
	v_lshl_add_u64 v[40:41], s[8:9], 0, v[22:23]
	s_nop 0
	v_addc_co_u32_e64 v9, s[2:3], 0, v43, s[2:3]
	v_add_co_u32_e64 v52, s[2:3], s38, v40
	v_lshl_add_u64 v[36:37], s[8:9], 0, v[28:29]
	s_nop 0
	v_addc_co_u32_e64 v53, s[2:3], 0, v41, s[2:3]
	v_add_co_u32_e64 v58, s[2:3], s39, v40
	global_load_dwordx2 v[60:61], v[36:37], off offset:-256
	s_nop 0
	v_addc_co_u32_e64 v59, s[2:3], 0, v41, s[2:3]
	v_add_co_u32_e32 v62, vcc, 0x6d01000, v40
	v_add_co_u32_e64 v46, s[2:3], s40, v42
	s_nop 0
	v_addc_co_u32_e32 v63, vcc, 0, v41, vcc
	v_addc_co_u32_e64 v47, s[2:3], 0, v43, s[2:3]
	v_add_co_u32_e64 v68, s[2:3], s42, v40
	v_add_co_u32_e32 v40, vcc, 0x16500000, v42
	s_nop 0
	v_addc_co_u32_e64 v69, s[2:3], 0, v41, s[2:3]
	global_load_dwordx2 v[62:63], v[62:63], off
	v_addc_co_u32_e32 v41, vcc, 0, v43, vcc
	global_load_dwordx2 v[70:71], v[40:41], off
	v_lshl_add_u64 v[44:45], s[8:9], 0, v[24:25]
	v_add_co_u32_e32 v42, vcc, 0x1e500000, v44
	s_add_i32 s43, s43, -4
	s_nop 0
	v_addc_co_u32_e32 v43, vcc, 0, v45, vcc
	global_load_dword v75, v[42:43], off
	v_lshl_add_u64 v[22:23], v[22:23], 0, s[22:23]
	v_lshl_add_u64 v[24:25], v[24:25], 0, s[24:25]
	v_lshl_add_u64 v[26:27], v[26:27], 0, s[10:11]
	v_lshl_add_u64 v[28:29], v[28:29], 0, s[26:27]
	s_cmp_eq_u32 s43, 0
	s_waitcnt vmcnt(3)
	v_lshlrev_b32_e32 v45, 16, v61
	v_lshlrev_b32_e32 v44, 16, v60
	v_and_b32_e32 v61, 0xffff0000, v61
	v_and_b32_e32 v60, 0xffff0000, v60
	v_pk_add_f32 v[72:73], v[44:45], v[60:61]
	s_waitcnt vmcnt(2)
	v_lshlrev_b32_e32 v49, 16, v62
	v_add_f32_e32 v4, v72, v73
	v_and_b32_e32 v57, 0xffff0000, v63
	s_waitcnt vmcnt(1)
	v_lshlrev_b32_e32 v77, 16, v70
	v_add_f32_dpp v73, v4, v4 quad_perm:[1,0,3,2] row_mask:0xf bank_mask:0xf bound_ctrl:1
	v_and_b32_e32 v78, 0xffff0000, v70
	v_lshlrev_b32_e32 v79, 16, v71
	v_and_b32_e32 v80, 0xffff0000, v71
	v_mov_b32_e32 v16, v49
	v_pk_add_f32 v[70:71], v[56:57], v[56:57] op_sel:[0,1] op_sel_hi:[1,0] neg_lo:[0,1] neg_hi:[0,1]
	v_mov_b32_e32 v6, v57
	v_mov_b32_e32 v76, v57
	v_add_f32_dpp v57, v73, v73 quad_perm:[2,3,0,1] row_mask:0xf bank_mask:0xf bound_ctrl:1
	v_mov_b32_e32 v34, v49
	v_mov_b32_e32 v56, v49
	v_pk_add_f32 v[48:49], v[48:49], v[16:17] neg_lo:[0,1] neg_hi:[0,1]
	v_add_f32_dpp v16, v57, v57 row_half_mirror row_mask:0xf bank_mask:0xf bound_ctrl:1
	v_and_b32_e32 v51, 0xffff0000, v62
	v_lshlrev_b32_e32 v55, 16, v63
	v_add_f32_dpp v16, v16, v16 row_ror:8 row_mask:0xf bank_mask:0xf bound_ctrl:1
	v_fmac_f32_e32 v44, 0xbc800000, v16
	v_fmac_f32_e32 v60, 0xbc800000, v16
	v_fmac_f32_e32 v45, 0xbc800000, v16
	v_fmac_f32_e32 v61, 0xbc800000, v16
	v_fma_f32 v16, v44, v44, 0
	v_fmac_f32_e32 v16, v60, v60
	v_fmac_f32_e32 v16, v45, v45
	v_fmac_f32_e32 v16, v61, v61
	v_pk_add_f32 v[62:63], v[50:51], v[50:51] op_sel:[0,1] op_sel_hi:[1,0] neg_lo:[0,1] neg_hi:[0,1]
	v_mov_b32_e32 v50, v55
	v_add_f32_dpp v16, v16, v16 quad_perm:[1,0,3,2] row_mask:0xf bank_mask:0xf bound_ctrl:1
	v_mov_b32_e32 v4, v51
	v_mov_b32_e32 v72, v51
	v_add_f32_dpp v16, v16, v16 quad_perm:[2,3,0,1] row_mask:0xf bank_mask:0xf bound_ctrl:1
	v_pk_add_f32 v[50:51], v[54:55], v[50:51] neg_lo:[0,1] neg_hi:[0,1]
	v_mov_b32_e32 v32, v55
	v_add_f32_dpp v16, v16, v16 row_half_mirror row_mask:0xf bank_mask:0xf bound_ctrl:1
	v_mov_b32_e32 v74, v55
	s_nop 0
	v_add_f32_dpp v16, v16, v16 row_ror:8 row_mask:0xf bank_mask:0xf bound_ctrl:1
	v_fmamk_f32 v16, v16, 0x3c800000, v65
	v_mul_f32_e32 v49, 0x4b800000, v16
	v_cmp_gt_f32_e32 vcc, s34, v16
	s_nop 1
	v_cndmask_b32_e32 v16, v16, v49, vcc
	v_rsq_f32_e32 v16, v16
	s_nop 0
	v_mul_f32_e32 v49, 0x45800000, v16
	v_cndmask_b32_e32 v16, v16, v49, vcc
	v_mul_f32_e32 v45, v45, v16
	v_mul_f32_e32 v49, v44, v16
	v_mul_f32_e32 v63, v60, v16
	v_mul_f32_e32 v71, v61, v16
	v_mov_b32_e32 v51, v45
	v_pk_fma_f32 v[44:45], v[10:11], v[48:49], v[34:35]
	v_pk_fma_f32 v[48:49], v[0:1], v[62:63], v[4:5]
	v_pk_fma_f32 v[50:51], v[30:31], v[50:51], v[32:33]
	v_pk_fma_f32 v[54:55], v[2:3], v[70:71], v[6:7]
	s_waitcnt vmcnt(0)
	v_fmac_f32_e32 v45, v75, v44
	v_fmac_f32_e32 v49, v75, v48
	v_fmac_f32_e32 v51, v75, v50
	v_fmac_f32_e32 v55, v75, v54
	v_mul_f32_e32 v4, v45, v77
	v_mul_f32_e32 v6, v49, v78
	v_mul_f32_e32 v16, v51, v79
	v_mul_f32_e32 v32, v55, v80
	v_cvt_pk_bf16_f32 v44, v4, v6
	v_cvt_pk_bf16_f32 v45, v16, v32
	global_store_dwordx2 v[8:9], v[44:45], off offset:-4096 nt
	global_load_dwordx2 v[44:45], v[36:37], off offset:-128
	s_nop 0
	global_load_dwordx2 v[40:41], v[40:41], off offset:2048
	s_nop 0
	global_load_dwordx2 v[48:49], v[52:53], off offset:3072
	global_load_dword v61, v[42:43], off offset:64
	s_waitcnt vmcnt(3)
	v_lshlrev_b32_e32 v51, 16, v45
	v_lshlrev_b32_e32 v50, 16, v44
	v_and_b32_e32 v45, 0xffff0000, v45
	v_and_b32_e32 v44, 0xffff0000, v44
	s_waitcnt vmcnt(1)
	v_and_b32_e32 v73, 0xffff0000, v48
	v_lshlrev_b32_e32 v63, 16, v40
	v_and_b32_e32 v71, 0xffff0000, v40
	v_lshlrev_b32_e32 v78, 16, v41
	v_and_b32_e32 v79, 0xffff0000, v41
	v_lshlrev_b32_e32 v57, 16, v48
	v_lshlrev_b32_e32 v75, 16, v49
	v_and_b32_e32 v77, 0xffff0000, v49
	v_pk_add_f32 v[40:41], v[50:51], v[44:45]
	v_pk_add_f32 v[48:49], v[72:73], v[72:73] op_sel:[0,1] op_sel_hi:[1,0] neg_lo:[0,1] neg_hi:[0,1]
	v_mov_b32_e32 v16, v57
	v_add_f32_e32 v49, v40, v41
	v_pk_add_f32 v[40:41], v[56:57], v[16:17] neg_lo:[0,1] neg_hi:[0,1]
	v_mov_b32_e32 v52, v75
	v_add_f32_dpp v16, v49, v49 quad_perm:[1,0,3,2] row_mask:0xf bank_mask:0xf bound_ctrl:1
	v_pk_add_f32 v[54:55], v[76:77], v[76:77] op_sel:[0,1] op_sel_hi:[1,0] neg_lo:[0,1] neg_hi:[0,1]
	v_pk_add_f32 v[52:53], v[74:75], v[52:53] neg_lo:[0,1] neg_hi:[0,1]
	v_add_f32_dpp v16, v16, v16 quad_perm:[2,3,0,1] row_mask:0xf bank_mask:0xf bound_ctrl:1
	v_mov_b32_e32 v34, v57
	v_mov_b32_e32 v4, v73
	v_add_f32_dpp v16, v16, v16 row_half_mirror row_mask:0xf bank_mask:0xf bound_ctrl:1
	v_mov_b32_e32 v32, v75
	v_mov_b32_e32 v6, v77
	v_add_f32_dpp v16, v16, v16 row_ror:8 row_mask:0xf bank_mask:0xf bound_ctrl:1
	v_fmac_f32_e32 v50, 0xbc800000, v16
	v_fmac_f32_e32 v44, 0xbc800000, v16
	v_fmac_f32_e32 v51, 0xbc800000, v16
	v_fmac_f32_e32 v45, 0xbc800000, v16
	v_fma_f32 v16, v50, v50, 0
	v_fmac_f32_e32 v16, v44, v44
	v_fmac_f32_e32 v16, v51, v51
	v_fmac_f32_e32 v16, v45, v45
	v_mov_b32_e32 v62, v73
	v_mov_b32_e32 v60, v57
	v_add_f32_dpp v16, v16, v16 quad_perm:[1,0,3,2] row_mask:0xf bank_mask:0xf bound_ctrl:1
	v_mov_b32_e32 v70, v75
	v_mov_b32_e32 v72, v77
	v_add_f32_dpp v16, v16, v16 quad_perm:[2,3,0,1] row_mask:0xf bank_mask:0xf bound_ctrl:1
	s_nop 1
	v_add_f32_dpp v16, v16, v16 row_half_mirror row_mask:0xf bank_mask:0xf bound_ctrl:1
	s_nop 1
	v_add_f32_dpp v16, v16, v16 row_ror:8 row_mask:0xf bank_mask:0xf bound_ctrl:1
	v_fmamk_f32 v16, v16, 0x3c800000, v65
	v_mul_f32_e32 v41, 0x4b800000, v16
	v_cmp_gt_f32_e32 vcc, s34, v16
	s_nop 1
	v_cndmask_b32_e32 v16, v16, v41, vcc
	v_rsq_f32_e32 v16, v16
	s_nop 0
	v_mul_f32_e32 v41, 0x45800000, v16
	v_cndmask_b32_e32 v16, v16, v41, vcc
	v_mul_f32_e32 v41, v50, v16
	v_mul_f32_e32 v49, v44, v16
	v_mul_f32_e32 v53, v51, v16
	v_mul_f32_e32 v55, v45, v16
	v_pk_fma_f32 v[40:41], v[10:11], v[40:41], v[34:35]
	v_pk_fma_f32 v[44:45], v[0:1], v[48:49], v[4:5]
	v_pk_fma_f32 v[48:49], v[30:31], v[52:53], v[32:33]
	v_pk_fma_f32 v[50:51], v[2:3], v[54:55], v[6:7]
	s_waitcnt vmcnt(0)
	v_fmac_f32_e32 v41, v61, v40
	v_fmac_f32_e32 v45, v61, v44
	v_fmac_f32_e32 v49, v61, v48
	v_fmac_f32_e32 v51, v61, v50
	v_mul_f32_e32 v4, v41, v63
	v_mul_f32_e32 v6, v45, v71
	v_mul_f32_e32 v16, v49, v78
	v_mul_f32_e32 v32, v51, v79
	v_cvt_pk_bf16_f32 v40, v4, v6
	v_cvt_pk_bf16_f32 v41, v16, v32
	global_store_dwordx2 v[38:39], v[40:41], off offset:2048 nt
	global_load_dwordx2 v[38:39], v[36:37], off
	s_nop 0
	global_load_dwordx2 v[40:41], v[46:47], off
	global_load_dwordx2 v[44:45], v[58:59], off offset:2048
	global_load_dword v54, v[42:43], off offset:128
	s_waitcnt vmcnt(3)
	v_lshlrev_b32_e32 v49, 16, v39
	v_lshlrev_b32_e32 v48, 16, v38
	v_and_b32_e32 v39, 0xffff0000, v39
	v_and_b32_e32 v38, 0xffff0000, v38
	s_waitcnt vmcnt(1)
	v_and_b32_e32 v63, 0xffff0000, v44
	v_lshlrev_b32_e32 v55, 16, v40
	v_and_b32_e32 v56, 0xffff0000, v40
	v_lshlrev_b32_e32 v57, 16, v41
	v_and_b32_e32 v58, 0xffff0000, v41
	v_lshlrev_b32_e32 v61, 16, v44
	v_lshlrev_b32_e32 v71, 16, v45
	v_and_b32_e32 v73, 0xffff0000, v45
	v_pk_add_f32 v[40:41], v[48:49], v[38:39]
	v_pk_add_f32 v[44:45], v[62:63], v[62:63] op_sel:[0,1] op_sel_hi:[1,0] neg_lo:[0,1] neg_hi:[0,1]
	v_mov_b32_e32 v16, v61
	v_add_f32_e32 v45, v40, v41
	v_pk_add_f32 v[40:41], v[60:61], v[16:17] neg_lo:[0,1] neg_hi:[0,1]
	v_mov_b32_e32 v50, v71
	v_add_f32_dpp v16, v45, v45 quad_perm:[1,0,3,2] row_mask:0xf bank_mask:0xf bound_ctrl:1
	v_pk_add_f32 v[52:53], v[72:73], v[72:73] op_sel:[0,1] op_sel_hi:[1,0] neg_lo:[0,1] neg_hi:[0,1]
	v_pk_add_f32 v[50:51], v[70:71], v[50:51] neg_lo:[0,1] neg_hi:[0,1]
	v_add_f32_dpp v16, v16, v16 quad_perm:[2,3,0,1] row_mask:0xf bank_mask:0xf bound_ctrl:1
	v_mov_b32_e32 v34, v61
	v_mov_b32_e32 v4, v63
	v_add_f32_dpp v16, v16, v16 row_half_mirror row_mask:0xf bank_mask:0xf bound_ctrl:1
	v_mov_b32_e32 v32, v71
	v_mov_b32_e32 v6, v73
	v_add_f32_dpp v16, v16, v16 row_ror:8 row_mask:0xf bank_mask:0xf bound_ctrl:1
	v_fmac_f32_e32 v48, 0xbc800000, v16
	v_fmac_f32_e32 v38, 0xbc800000, v16
	v_fmac_f32_e32 v49, 0xbc800000, v16
	v_fmac_f32_e32 v39, 0xbc800000, v16
	v_fma_f32 v16, v48, v48, 0
	v_fmac_f32_e32 v16, v38, v38
	v_fmac_f32_e32 v16, v49, v49
	v_fmac_f32_e32 v16, v39, v39
	s_nop 1
	v_add_f32_dpp v16, v16, v16 quad_perm:[1,0,3,2] row_mask:0xf bank_mask:0xf bound_ctrl:1
	s_nop 1
	v_add_f32_dpp v16, v16, v16 quad_perm:[2,3,0,1] row_mask:0xf bank_mask:0xf bound_ctrl:1
	s_nop 1
	v_add_f32_dpp v16, v16, v16 row_half_mirror row_mask:0xf bank_mask:0xf bound_ctrl:1
	s_nop 1
	v_add_f32_dpp v16, v16, v16 row_ror:8 row_mask:0xf bank_mask:0xf bound_ctrl:1
	v_fmamk_f32 v16, v16, 0x3c800000, v65
	v_mul_f32_e32 v41, 0x4b800000, v16
	v_cmp_gt_f32_e32 vcc, s34, v16
	s_nop 1
	v_cndmask_b32_e32 v16, v16, v41, vcc
	v_rsq_f32_e32 v16, v16
	s_nop 0
	v_mul_f32_e32 v41, 0x45800000, v16
	v_cndmask_b32_e32 v16, v16, v41, vcc
	v_mul_f32_e32 v41, v48, v16
	v_mul_f32_e32 v45, v38, v16
	v_mul_f32_e32 v51, v49, v16
	v_mul_f32_e32 v53, v39, v16
	v_pk_fma_f32 v[38:39], v[10:11], v[40:41], v[34:35]
	v_pk_fma_f32 v[40:41], v[0:1], v[44:45], v[4:5]
	v_pk_fma_f32 v[44:45], v[30:31], v[50:51], v[32:33]
	v_pk_fma_f32 v[48:49], v[2:3], v[52:53], v[6:7]
	s_waitcnt vmcnt(0)
	v_fmac_f32_e32 v39, v54, v38
	v_fmac_f32_e32 v41, v54, v40
	v_fmac_f32_e32 v45, v54, v44
	v_fmac_f32_e32 v49, v54, v48
	v_mul_f32_e32 v4, v39, v55
	v_mul_f32_e32 v6, v41, v56
	v_mul_f32_e32 v16, v45, v57
	v_mul_f32_e32 v32, v49, v58
	v_cvt_pk_bf16_f32 v38, v4, v6
	v_cvt_pk_bf16_f32 v39, v16, v32
	global_store_dwordx2 v[8:9], v[38:39], off nt
	global_load_dwordx2 v[36:37], v[36:37], off offset:128
	s_nop 0
	global_load_dwordx2 v[40:41], v[46:47], off offset:2048
	global_load_dwordx2 v[38:39], v[68:69], off offset:1024
	global_load_dword v56, v[42:43], off offset:192
	v_mov_b32_e32 v44, v63
	v_mov_b32_e32 v42, v61
	v_mov_b32_e32 v46, v71
	v_mov_b32_e32 v48, v73
	s_waitcnt vmcnt(3)
	v_lshlrev_b32_e32 v51, 16, v37
	v_lshlrev_b32_e32 v50, 16, v36
	v_and_b32_e32 v37, 0xffff0000, v37
	v_and_b32_e32 v36, 0xffff0000, v36
	s_waitcnt vmcnt(2)
	v_lshlrev_b32_e32 v57, 16, v40
	v_and_b32_e32 v58, 0xffff0000, v40
	v_lshlrev_b32_e32 v59, 16, v41
	v_and_b32_e32 v60, 0xffff0000, v41
	s_waitcnt vmcnt(1)
	v_lshlrev_b32_e32 v43, 16, v38
	v_and_b32_e32 v45, 0xffff0000, v38
	v_pk_add_f32 v[40:41], v[50:51], v[36:37]
	v_mov_b32_e32 v16, v43
	v_pk_add_f32 v[52:53], v[44:45], v[44:45] op_sel:[0,1] op_sel_hi:[1,0] neg_lo:[0,1] neg_hi:[0,1]
	v_mov_b32_e32 v4, v45
	v_add_f32_e32 v45, v40, v41
	v_pk_add_f32 v[40:41], v[42:43], v[16:17] neg_lo:[0,1] neg_hi:[0,1]
	v_lshlrev_b32_e32 v47, 16, v39
	v_add_f32_dpp v16, v45, v45 quad_perm:[1,0,3,2] row_mask:0xf bank_mask:0xf bound_ctrl:1
	v_and_b32_e32 v49, 0xffff0000, v39
	v_mov_b32_e32 v44, v47
	v_add_f32_dpp v16, v16, v16 quad_perm:[2,3,0,1] row_mask:0xf bank_mask:0xf bound_ctrl:1
	v_mov_b32_e32 v34, v43
	v_pk_add_f32 v[54:55], v[48:49], v[48:49] op_sel:[0,1] op_sel_hi:[1,0] neg_lo:[0,1] neg_hi:[0,1]
	v_add_f32_dpp v16, v16, v16 row_half_mirror row_mask:0xf bank_mask:0xf bound_ctrl:1
	v_pk_add_f32 v[42:43], v[46:47], v[44:45] neg_lo:[0,1] neg_hi:[0,1]
	v_mov_b32_e32 v32, v47
	v_add_f32_dpp v16, v16, v16 row_ror:8 row_mask:0xf bank_mask:0xf bound_ctrl:1
	v_fmac_f32_e32 v50, 0xbc800000, v16
	v_fmac_f32_e32 v36, 0xbc800000, v16
	v_fmac_f32_e32 v51, 0xbc800000, v16
	v_fmac_f32_e32 v37, 0xbc800000, v16
	v_fma_f32 v16, v50, v50, 0
	v_fmac_f32_e32 v16, v36, v36
	v_fmac_f32_e32 v16, v51, v51
	v_fmac_f32_e32 v16, v37, v37
	v_mov_b32_e32 v6, v49
	s_nop 0
	v_add_f32_dpp v16, v16, v16 quad_perm:[1,0,3,2] row_mask:0xf bank_mask:0xf bound_ctrl:1
	s_nop 1
	v_add_f32_dpp v16, v16, v16 quad_perm:[2,3,0,1] row_mask:0xf bank_mask:0xf bound_ctrl:1
	s_nop 1
	v_add_f32_dpp v16, v16, v16 row_half_mirror row_mask:0xf bank_mask:0xf bound_ctrl:1
	s_nop 1
	v_add_f32_dpp v16, v16, v16 row_ror:8 row_mask:0xf bank_mask:0xf bound_ctrl:1
	v_fmamk_f32 v16, v16, 0x3c800000, v65
	v_mul_f32_e32 v41, 0x4b800000, v16
	v_cmp_gt_f32_e32 vcc, s34, v16
	s_nop 1
	v_cndmask_b32_e32 v16, v16, v41, vcc
	v_rsq_f32_e32 v16, v16
	s_nop 0
	v_mul_f32_e32 v41, 0x45800000, v16
	v_cndmask_b32_e32 v16, v16, v41, vcc
	v_mul_f32_e32 v41, v50, v16
	v_mul_f32_e32 v53, v36, v16
	v_mul_f32_e32 v43, v51, v16
	v_mul_f32_e32 v55, v37, v16
	v_pk_fma_f32 v[36:37], v[10:11], v[40:41], v[34:35]
	v_pk_fma_f32 v[40:41], v[0:1], v[52:53], v[4:5]
	v_pk_fma_f32 v[42:43], v[30:31], v[42:43], v[32:33]
	v_pk_fma_f32 v[44:45], v[2:3], v[54:55], v[6:7]
	s_waitcnt vmcnt(0)
	v_fmac_f32_e32 v37, v56, v36
	v_fmac_f32_e32 v41, v56, v40
	v_fmac_f32_e32 v43, v56, v42
	v_fmac_f32_e32 v45, v56, v44
	v_mul_f32_e32 v4, v37, v57
	v_mul_f32_e32 v6, v41, v58
	v_mul_f32_e32 v16, v43, v59
	v_mul_f32_e32 v32, v45, v60
	v_cvt_pk_bf16_f32 v36, v4, v6
	v_cvt_pk_bf16_f32 v37, v16, v32
	global_store_dwordx2 v[8:9], v[36:37], off offset:2048 nt
	s_cbranch_scc0 .LBB0_639
	v_readlane_b32 s2, v254, 7
	v_readlane_b32 s3, v254, 8
	v_lshl_add_u64 v[20:21], v[20:21], 0, s[16:17]
	s_nop 0
	v_lshl_add_u64 v[12:13], v[12:13], 0, s[2:3]
	v_cmp_lt_u64_e32 vcc, s[28:29], v[12:13]
	s_or_b64 s[18:19], vcc, s[18:19]
	s_andn2_b64 exec, exec, s[18:19]
	s_cbranch_execnz .LBB0_636

.LBB0_780:
	s_cmp_lt_u32 s41, 18
	s_cbranch_scc0 .Lep9_gate
	s_lshl_b32 s7, s42, 8
	s_add_i32 s7, s7, s35
	s_lshl_b32 s9, s41, 8
	s_cmp_lt_i32 s41, 18
	v_mbcnt_lo_u32_b32 v155, -1, 0
	v_mbcnt_hi_u32_b32 v155, -1, v155
	s_cselect_b32 s14, 0, 0xffffee00
	v_and_or_b32 v158, v155, 15, s7
	s_cselect_b32 s7, s30, s34
	v_mov_b32_e32 v145, s7
	s_movk_i32 s7, 0x1200
	s_cselect_b32 s15, s29, s31
	s_cselect_b32 s7, s7, 0x800
	v_ashrrev_i32_e32 v155, 1, v155
	s_or_b32 s9, s9, s36
	v_and_b32_e32 v155, -8, v155
	s_add_i32 s9, s9, s14
	v_add_u32_e32 v156, s9, v155
	v_mov_b32_e32 v144, s15
	v_ashrrev_i32_e32 v157, 31, v156
	v_lshl_add_u64 v[144:145], v[156:157], 1, v[144:145]
	v_mad_i64_i32 v[156:157], s[14:15], s7, v158, 0
	v_lshl_add_u64 v[156:157], v[156:157], 1, v[144:145]
	v_cvt_pk_bf16_f32 v124, v124, v125
	v_cvt_pk_bf16_f32 v125, v126, v127
	v_cvt_pk_bf16_f32 v126, v120, v121
	v_cvt_pk_bf16_f32 v127, v122, v123
	global_store_dwordx4 v[156:157], v[124:127], off
	v_cvt_pk_bf16_f32 v112, v112, v113
	v_cvt_pk_bf16_f32 v113, v114, v115
	v_cvt_pk_bf16_f32 v114, v104, v105
	v_or_b32_e32 v104, 16, v158
	v_mad_i64_i32 v[104:105], s[14:15], s7, v104, 0
	v_cvt_pk_bf16_f32 v115, v106, v107
	global_store_dwordx4 v[156:157], v[112:115], off offset:256
	s_andn2_b64 vcc, exec, s[2:3]
	s_mov_b64 s[2:3], -1
	v_lshl_add_u64 v[112:113], v[104:105], 1, v[144:145]
	v_cvt_pk_bf16_f32 v104, v116, v117
	v_cvt_pk_bf16_f32 v105, v118, v119
	v_cvt_pk_bf16_f32 v106, v108, v109
	v_cvt_pk_bf16_f32 v107, v110, v111
	global_store_dwordx4 v[112:113], v[104:107], off
	v_cvt_pk_bf16_f32 v96, v96, v97
	v_cvt_pk_bf16_f32 v97, v98, v99
	v_cvt_pk_bf16_f32 v98, v88, v89
	v_or_b32_e32 v88, 32, v158
	v_mad_i64_i32 v[88:89], s[14:15], s7, v88, 0
	v_cvt_pk_bf16_f32 v99, v90, v91
	global_store_dwordx4 v[112:113], v[96:99], off offset:256
	s_nop 1
	v_lshl_add_u64 v[96:97], v[88:89], 1, v[144:145]
	v_cvt_pk_bf16_f32 v88, v100, v101
	v_cvt_pk_bf16_f32 v89, v102, v103
	v_cvt_pk_bf16_f32 v90, v92, v93
	v_cvt_pk_bf16_f32 v91, v94, v95
	global_store_dwordx4 v[96:97], v[88:91], off
	v_cvt_pk_bf16_f32 v80, v80, v81
	v_cvt_pk_bf16_f32 v81, v82, v83
	v_cvt_pk_bf16_f32 v82, v72, v73
	v_or_b32_e32 v72, 48, v158
	v_mad_i64_i32 v[72:73], s[14:15], s7, v72, 0
	v_cvt_pk_bf16_f32 v83, v74, v75
	global_store_dwordx4 v[96:97], v[80:83], off offset:256
	s_nop 1
	v_lshl_add_u64 v[80:81], v[72:73], 1, v[144:145]
	v_cvt_pk_bf16_f32 v72, v84, v85
	v_cvt_pk_bf16_f32 v73, v86, v87
	v_cvt_pk_bf16_f32 v74, v76, v77
	v_cvt_pk_bf16_f32 v75, v78, v79
	global_store_dwordx4 v[80:81], v[72:75], off
	v_cvt_pk_bf16_f32 v68, v68, v69
	v_cvt_pk_bf16_f32 v69, v70, v71
	v_cvt_pk_bf16_f32 v70, v64, v65
	v_add_u32_e32 v64, 0x80, v158
	v_mad_i64_i32 v[64:65], s[14:15], s7, v64, 0
	v_cvt_pk_bf16_f32 v71, v66, v67
	global_store_dwordx4 v[80:81], v[68:71], off offset:256
	v_lshl_add_u64 v[64:65], v[64:65], 1, v[144:145]
	v_cvt_pk_bf16_f32 v60, v60, v61
	v_cvt_pk_bf16_f32 v61, v62, v63
	v_cvt_pk_bf16_f32 v62, v56, v57
	v_cvt_pk_bf16_f32 v63, v58, v59
	global_store_dwordx4 v[64:65], v[60:63], off
	v_cvt_pk_bf16_f32 v48, v48, v49
	v_cvt_pk_bf16_f32 v49, v50, v51
	v_cvt_pk_bf16_f32 v50, v40, v41
	v_add_u32_e32 v40, 0x90, v158
	v_mad_i64_i32 v[40:41], s[14:15], s7, v40, 0
	v_cvt_pk_bf16_f32 v51, v42, v43
	global_store_dwordx4 v[64:65], v[48:51], off offset:256
	s_nop 1
	v_lshl_add_u64 v[48:49], v[40:41], 1, v[144:145]
	v_cvt_pk_bf16_f32 v40, v52, v53
	v_cvt_pk_bf16_f32 v41, v54, v55
	v_cvt_pk_bf16_f32 v42, v44, v45
	v_cvt_pk_bf16_f32 v43, v46, v47
	global_store_dwordx4 v[48:49], v[40:43], off
	v_cvt_pk_bf16_f32 v32, v32, v33
	v_cvt_pk_bf16_f32 v33, v34, v35
	v_cvt_pk_bf16_f32 v34, v24, v25
	v_add_u32_e32 v24, 0xa0, v158
	v_mad_i64_i32 v[24:25], s[14:15], s7, v24, 0
	v_cvt_pk_bf16_f32 v35, v26, v27
	global_store_dwordx4 v[48:49], v[32:35], off offset:256
	s_nop 1
	v_lshl_add_u64 v[32:33], v[24:25], 1, v[144:145]
	v_cvt_pk_bf16_f32 v24, v36, v37
	v_cvt_pk_bf16_f32 v25, v38, v39
	v_cvt_pk_bf16_f32 v26, v28, v29
	v_cvt_pk_bf16_f32 v27, v30, v31
	global_store_dwordx4 v[32:33], v[24:27], off
	v_cvt_pk_bf16_f32 v16, v16, v17
	v_cvt_pk_bf16_f32 v17, v18, v19
	v_cvt_pk_bf16_f32 v18, v8, v9
	v_add_u32_e32 v8, 0xb0, v158
	v_mad_i64_i32 v[8:9], s[14:15], s7, v8, 0
	v_cvt_pk_bf16_f32 v19, v10, v11
	global_store_dwordx4 v[32:33], v[16:19], off offset:256
	s_nop 1
	v_lshl_add_u64 v[16:17], v[8:9], 1, v[144:145]
	v_cvt_pk_bf16_f32 v8, v20, v21
	v_cvt_pk_bf16_f32 v9, v22, v23
	v_cvt_pk_bf16_f32 v10, v12, v13
	v_cvt_pk_bf16_f32 v11, v14, v15
	global_store_dwordx4 v[16:17], v[8:11], off
	v_cvt_pk_bf16_f32 v4, v4, v5
	v_cvt_pk_bf16_f32 v5, v6, v7
	v_cvt_pk_bf16_f32 v6, v0, v1
	v_cvt_pk_bf16_f32 v7, v2, v3
	global_store_dwordx4 v[16:17], v[4:7], off offset:256
	s_branch .Lep9_join
.Lep9_gate:
	s_lshl_b32 s7, s42, 8
	s_add_i32 s7, s7, s35
	s_lshl_b32 s9, s41, 8
	s_cmp_lt_i32 s41, 18
	v_mbcnt_lo_u32_b32 v155, -1, 0
	v_mbcnt_hi_u32_b32 v155, -1, v155
	s_cselect_b32 s14, 0, 0xffffee00
	v_and_or_b32 v158, v155, 15, s7
	s_cselect_b32 s7, s30, s34
	v_mov_b32_e32 v145, s7
	s_movk_i32 s7, 0x1200
	s_cselect_b32 s15, s29, s31
	s_cselect_b32 s7, s7, 0x800
	v_ashrrev_i32_e32 v155, 1, v155
	s_or_b32 s9, s9, s36
	v_and_b32_e32 v155, -8, v155
	s_add_i32 s9, s9, s14
	v_add_u32_e32 v156, s9, v155
	v_mov_b32_e32 v144, s15
	v_ashrrev_i32_e32 v157, 31, v156
	v_lshl_add_u64 v[144:145], v[156:157], 1, v[144:145]
	v_mad_i64_i32 v[156:157], s[14:15], s7, v158, 0
	v_lshl_add_u64 v[156:157], v[156:157], 1, v[144:145]
	v_cvt_pk_bf16_f32 v124, v124, v125
	v_cvt_pk_bf16_f32 v125, v126, v127
	v_cvt_pk_bf16_f32 v126, v120, v121
	v_cvt_pk_bf16_f32 v127, v122, v123
	global_store_dwordx4 v[156:157], v[124:127], off nt
	v_cvt_pk_bf16_f32 v112, v112, v113
	v_cvt_pk_bf16_f32 v113, v114, v115
	v_cvt_pk_bf16_f32 v114, v104, v105
	v_or_b32_e32 v104, 16, v158
	v_mad_i64_i32 v[104:105], s[14:15], s7, v104, 0
	v_cvt_pk_bf16_f32 v115, v106, v107
	global_store_dwordx4 v[156:157], v[112:115], off offset:256 nt
	s_andn2_b64 vcc, exec, s[2:3]
	s_mov_b64 s[2:3], -1
	v_lshl_add_u64 v[112:113], v[104:105], 1, v[144:145]
	v_cvt_pk_bf16_f32 v104, v116, v117
	v_cvt_pk_bf16_f32 v105, v118, v119
	v_cvt_pk_bf16_f32 v106, v108, v109
	v_cvt_pk_bf16_f32 v107, v110, v111
	global_store_dwordx4 v[112:113], v[104:107], off nt
	v_cvt_pk_bf16_f32 v96, v96, v97
	v_cvt_pk_bf16_f32 v97, v98, v99
	v_cvt_pk_bf16_f32 v98, v88, v89
	v_or_b32_e32 v88, 32, v158
	v_mad_i64_i32 v[88:89], s[14:15], s7, v88, 0
	v_cvt_pk_bf16_f32 v99, v90, v91
	global_store_dwordx4 v[112:113], v[96:99], off offset:256 nt
	s_nop 1
	v_lshl_add_u64 v[96:97], v[88:89], 1, v[144:145]
	v_cvt_pk_bf16_f32 v88, v100, v101
	v_cvt_pk_bf16_f32 v89, v102, v103
	v_cvt_pk_bf16_f32 v90, v92, v93
	v_cvt_pk_bf16_f32 v91, v94, v95
	global_store_dwordx4 v[96:97], v[88:91], off nt
	v_cvt_pk_bf16_f32 v80, v80, v81
	v_cvt_pk_bf16_f32 v81, v82, v83
	v_cvt_pk_bf16_f32 v82, v72, v73
	v_or_b32_e32 v72, 48, v158
	v_mad_i64_i32 v[72:73], s[14:15], s7, v72, 0
	v_cvt_pk_bf16_f32 v83, v74, v75
	global_store_dwordx4 v[96:97], v[80:83], off offset:256 nt
	s_nop 1
	v_lshl_add_u64 v[80:81], v[72:73], 1, v[144:145]
	v_cvt_pk_bf16_f32 v72, v84, v85
	v_cvt_pk_bf16_f32 v73, v86, v87
	v_cvt_pk_bf16_f32 v74, v76, v77
	v_cvt_pk_bf16_f32 v75, v78, v79
	global_store_dwordx4 v[80:81], v[72:75], off nt
	v_cvt_pk_bf16_f32 v68, v68, v69
	v_cvt_pk_bf16_f32 v69, v70, v71
	v_cvt_pk_bf16_f32 v70, v64, v65
	v_add_u32_e32 v64, 0x80, v158
	v_mad_i64_i32 v[64:65], s[14:15], s7, v64, 0
	v_cvt_pk_bf16_f32 v71, v66, v67
	global_store_dwordx4 v[80:81], v[68:71], off offset:256 nt
	v_lshl_add_u64 v[64:65], v[64:65], 1, v[144:145]
	v_cvt_pk_bf16_f32 v60, v60, v61
	v_cvt_pk_bf16_f32 v61, v62, v63
	v_cvt_pk_bf16_f32 v62, v56, v57
	v_cvt_pk_bf16_f32 v63, v58, v59
	global_store_dwordx4 v[64:65], v[60:63], off nt
	v_cvt_pk_bf16_f32 v48, v48, v49
	v_cvt_pk_bf16_f32 v49, v50, v51
	v_cvt_pk_bf16_f32 v50, v40, v41
	v_add_u32_e32 v40, 0x90, v158
	v_mad_i64_i32 v[40:41], s[14:15], s7, v40, 0
	v_cvt_pk_bf16_f32 v51, v42, v43
	global_store_dwordx4 v[64:65], v[48:51], off offset:256 nt
	s_nop 1
	v_lshl_add_u64 v[48:49], v[40:41], 1, v[144:145]
	v_cvt_pk_bf16_f32 v40, v52, v53
	v_cvt_pk_bf16_f32 v41, v54, v55
	v_cvt_pk_bf16_f32 v42, v44, v45
	v_cvt_pk_bf16_f32 v43, v46, v47
	global_store_dwordx4 v[48:49], v[40:43], off nt
	v_cvt_pk_bf16_f32 v32, v32, v33
	v_cvt_pk_bf16_f32 v33, v34, v35
	v_cvt_pk_bf16_f32 v34, v24, v25
	v_add_u32_e32 v24, 0xa0, v158
	v_mad_i64_i32 v[24:25], s[14:15], s7, v24, 0
	v_cvt_pk_bf16_f32 v35, v26, v27
	global_store_dwordx4 v[48:49], v[32:35], off offset:256 nt
	s_nop 1
	v_lshl_add_u64 v[32:33], v[24:25], 1, v[144:145]
	v_cvt_pk_bf16_f32 v24, v36, v37
	v_cvt_pk_bf16_f32 v25, v38, v39
	v_cvt_pk_bf16_f32 v26, v28, v29
	v_cvt_pk_bf16_f32 v27, v30, v31
	global_store_dwordx4 v[32:33], v[24:27], off nt
	v_cvt_pk_bf16_f32 v16, v16, v17
	v_cvt_pk_bf16_f32 v17, v18, v19
	v_cvt_pk_bf16_f32 v18, v8, v9
	v_add_u32_e32 v8, 0xb0, v158
	v_mad_i64_i32 v[8:9], s[14:15], s7, v8, 0
	v_cvt_pk_bf16_f32 v19, v10, v11
	global_store_dwordx4 v[32:33], v[16:19], off offset:256 nt
	s_nop 1
	v_lshl_add_u64 v[16:17], v[8:9], 1, v[144:145]
	v_cvt_pk_bf16_f32 v8, v20, v21
	v_cvt_pk_bf16_f32 v9, v22, v23
	v_cvt_pk_bf16_f32 v10, v12, v13
	v_cvt_pk_bf16_f32 v11, v14, v15
	global_store_dwordx4 v[16:17], v[8:11], off nt
	v_cvt_pk_bf16_f32 v4, v4, v5
	v_cvt_pk_bf16_f32 v5, v6, v7
	v_cvt_pk_bf16_f32 v6, v0, v1
	v_cvt_pk_bf16_f32 v7, v2, v3
	global_store_dwordx4 v[16:17], v[4:7], off offset:256 nt
.Lep9_join:
	s_cbranch_vccnz .LBB0_773
	s_andn2_b64 vcc, exec, s[0:1]
	s_cbranch_vccnz .LBB0_772
	s_barrier
	s_branch .LBB0_772

.LBB0_1714:
	s_or_b64 exec, exec, s[8:9]
	v_pk_mul_f32 v[74:75], v[8:9], v[8:9]
	v_pk_mul_f32 v[76:77], v[12:13], v[12:13]
	v_pk_mul_f32 v[70:71], v[14:15], v[14:15]
	v_pk_mul_f32 v[72:73], v[10:11], v[10:11]
	v_mov_b32_e32 v78, v76
	v_mov_b32_e32 v79, v74
	v_mov_b32_e32 v74, v77
	v_mov_b32_e32 v76, v70
	v_mov_b32_e32 v77, v72
	v_mov_b32_e32 v72, v71
	v_pk_add_f32 v[70:71], v[78:79], v[74:75]
	v_pk_mul_f32 v[66:67], v[0:1], v[0:1]
	v_pk_mul_f32 v[68:69], v[4:5], v[4:5]
	v_pk_add_f32 v[70:71], v[76:77], v[70:71]
	v_pk_mul_f32 v[62:63], v[2:3], v[2:3]
	v_pk_mul_f32 v[64:65], v[6:7], v[6:7]
	v_pk_add_f32 v[70:71], v[72:73], v[70:71]
	v_mov_b32_e32 v72, v66
	v_mov_b32_e32 v73, v68
	v_mov_b32_e32 v68, v67
	v_mov_b32_e32 v66, v62
	v_mov_b32_e32 v67, v64
	v_mov_b32_e32 v64, v63
	v_pk_add_f32 v[62:63], v[72:73], v[68:69]
	s_and_b64 s[8:9], exec, vcc
	v_pk_add_f32 v[62:63], v[66:67], v[62:63]
	s_or_b64 s[6:7], s[8:9], s[6:7]
	v_pk_add_f32 v[62:63], v[64:65], v[62:63]
	v_add_f32_e32 v64, v70, v71
	v_add_f32_e32 v63, v63, v64
	v_add_f32_e32 v62, v62, v63
	ds_bpermute_b32 v63, v49, v62
	s_waitcnt lgkmcnt(0)
	v_add_f32_e32 v62, v62, v63
	ds_bpermute_b32 v63, v55, v62
	s_waitcnt lgkmcnt(0)
	v_add_f32_e32 v62, v62, v63
	ds_bpermute_b32 v63, v57, v62
	s_waitcnt lgkmcnt(0)
	v_add_f32_e32 v62, v62, v63
	ds_bpermute_b32 v63, v58, v62
	s_waitcnt lgkmcnt(0)
	v_add_f32_e32 v62, v62, v63
	ds_bpermute_b32 v63, v59, v62
	s_waitcnt lgkmcnt(0)
	v_add_f32_e32 v62, v62, v63
	ds_bpermute_b32 v63, v60, v62
	s_waitcnt lgkmcnt(0)
	v_add_f32_e32 v62, v62, v63
	v_fmamk_f32 v62, v62, 0x3a800000, v61
	v_mul_f32_e32 v63, 0x4b800000, v62
	v_cmp_gt_f32_e64 s[0:1], s10, v62
	s_nop 1
	v_cndmask_b32_e64 v62, v62, v63, s[0:1]
	v_rsq_f32_e32 v62, v62
	s_nop 0
	v_mul_f32_e32 v63, 0x45800000, v62
	v_cndmask_b32_e64 v62, v62, v63, s[0:1]
	v_pk_mul_f32 v[12:13], v[12:13], v[62:63] op_sel_hi:[1,0]
	v_pk_mul_f32 v[14:15], v[14:15], v[62:63] op_sel_hi:[1,0]
	v_pk_mul_f32 v[8:9], v[8:9], v[62:63] op_sel_hi:[1,0]
	v_pk_mul_f32 v[10:11], v[10:11], v[62:63] op_sel_hi:[1,0]
	v_pk_mul_f32 v[4:5], v[4:5], v[62:63] op_sel_hi:[1,0]
	v_pk_mul_f32 v[6:7], v[6:7], v[62:63] op_sel_hi:[1,0]
	v_pk_mul_f32 v[0:1], v[0:1], v[62:63] op_sel_hi:[1,0]
	v_pk_mul_f32 v[2:3], v[2:3], v[62:63] op_sel_hi:[1,0]
	v_pk_mul_f32 v[14:15], v[30:31], v[14:15]
	v_pk_mul_f32 v[12:13], v[28:29], v[12:13]
	v_pk_mul_f32 v[10:11], v[26:27], v[10:11]
	v_pk_mul_f32 v[8:9], v[24:25], v[8:9]
	v_pk_mul_f32 v[6:7], v[22:23], v[6:7]
	v_pk_mul_f32 v[4:5], v[20:21], v[4:5]
	v_pk_mul_f32 v[2:3], v[18:19], v[2:3]
	v_pk_mul_f32 v[0:1], v[16:17], v[0:1]
	global_store_dwordx4 v[52:53], v[12:15], off offset:-4096 nt
	global_store_dwordx4 v[52:53], v[8:11], off offset:-3072 nt
	global_store_dwordx4 v[52:53], v[4:7], off offset:-2048 nt
	global_store_dwordx4 v[52:53], v[0:3], off offset:-1024 nt
	v_lshl_add_u64 v[52:53], v[52:53], 0, s[2:3]
	s_waitcnt vmcnt(7)
	v_mov_b32_e32 v12, v32
	v_mov_b32_e32 v13, v33
	v_mov_b32_e32 v14, v34
	v_mov_b32_e32 v15, v35
	s_waitcnt vmcnt(6)
	v_mov_b32_e32 v8, v36
	v_mov_b32_e32 v9, v37
	v_mov_b32_e32 v10, v38
	v_mov_b32_e32 v11, v39
	s_waitcnt vmcnt(5)
	v_mov_b32_e32 v4, v40
	v_mov_b32_e32 v5, v41
	v_mov_b32_e32 v6, v42
	v_mov_b32_e32 v7, v43
	s_waitcnt vmcnt(4)
	v_mov_b32_e32 v0, v44
	v_mov_b32_e32 v1, v45
	v_mov_b32_e32 v2, v46
	v_mov_b32_e32 v3, v47
	s_andn2_b64 exec, exec, s[6:7]
	s_cbranch_execz .LBB0_1719
